# comb1 + attention fast path: softmax VALU interleaved into the wave's own QK^T/PV MFMA gaps (non-diagonal tiles)
# speedup vs baseline: 1.0096x; 1.0051x over previous
; #define LAS __attribute__((address_space(3)))
; __device__ __forceinline__ void finishSM(f32x16& p0, f32x16& p1, float alpha, float& l_reg, bf16x8& pa0, bf16x8& pa1, bf16x8& pa2, bf16x8& pa3) {
; #pragma unroll
;     for (int r = 0; r < 16; ++r) p1[r] = __builtin_amdgcn_exp2f(p1[r]);
;     f32x4 s4 = (f32x4){p0[0], p0[1], p0[2], p0[3]} + (f32x4){p1[0], p1[1], p1[2], p1[3]};
; #pragma unroll
;     for (int r = 4; r < 16; r += 4) s4 += (f32x4){p0[r], p0[r + 1], p0[r + 2], p0[r + 3]} + (f32x4){p1[r], p1[r + 1], p1[r + 2], p1[r + 3]};
;     float ps = (s4[0] + s4[1]) + (s4[2] + s4[3]);
;     { auto rr = __builtin_amdgcn_permlane32_swap(__float_as_uint(ps), __float_as_uint(ps), false, false); ps = __uint_as_float(rr[0]) + __uint_as_float(rr[1]); }
;     l_reg = l_reg * alpha + ps;
;     ...
;     PK4(p0, 0, pa0); PK4(p0, 8, pa1); PK4(p1, 0, pa2); PK4(p1, 8, pa3);
;     ...
; }
; template <int KB>
; __device__ __forceinline__ void qkt(f32x16& p0, f32x16& p1, lptr K_lds, int r32, int hi, const bf16x8* qr, const LAS float* blk) {
;     { const LAS f32x4* bp = (const LAS f32x4*)blk;
;       const f32x4 a0 = bp[0], a1 = bp[2], a2 = bp[4], a3 = bp[6], c0 = bp[8], c1 = bp[10], c2 = bp[12], c3 = bp[14];
;       p0 = (f32x16){a0[0], a0[1], a0[2], a0[3], a1[0], a1[1], a1[2], a1[3], a2[0], a2[1], a2[2], a2[3], a3[0], a3[1], a3[2], a3[3]};
;       p1 = (f32x16){c0[0], c0[1], c0[2], c0[3], c1[0], c1[1], c1[2], c1[3], c2[0], c2[1], c2[2], c2[3], c3[0], c3[1], c3[2], c3[3]}; }
;     lptr kb[4];
; #pragma unroll
;     for (int dd = 0; dd < 4; ++dd) kb[dd] = K_lds + KB * SHM_K + KSWZ(r32, (dd * 16 + hi * 8) * 2);
; #pragma unroll
;     for (int d0 = 0; d0 < 8; ++d0) { lptr a = kb[d0 & 3] + (d0 >> 2) * 128;
;         bf16x8 b0 = *(const LAS bf16x8*)(a);
;         bf16x8 b1 = *(const LAS bf16x8*)(a + 32 * 256);
;         p0 = __builtin_amdgcn_mfma_f32_32x32x16_bf16(b0, qr[d0], p0, 0, 0, 0);
;         p1 = __builtin_amdgcn_mfma_f32_32x32x16_bf16(b1, qr[d0], p1, 0, 0, 0); }
; }
.LBB0_529:
	s_add_u32 s12, s84, 0x8000
	s_addc_u32 s13, s85, 0
	s_add_u32 s14, s84, 0xa000
	s_addc_u32 s15, s85, 0
	s_add_u32 s16, s82, 0x8000
	s_addc_u32 s17, s83, 0
	s_add_u32 s18, s82, 0xa000
	s_addc_u32 s19, s83, 0
	v_lshl_add_u64 v[178:179], s[12:13], 0, v[198:199]
	v_lshl_add_u64 v[182:183], s[14:15], 0, v[198:199]
	v_lshl_add_u64 v[186:187], s[16:17], 0, v[198:199]
	v_lshl_add_u64 v[190:191], s[18:19], 0, v[198:199]
	global_load_dwordx4 v[178:181], v[178:179], off
	global_load_dwordx4 v[182:185], v[182:183], off
	global_load_dwordx4 v[186:189], v[186:187], off
	global_load_dwordx4 v[190:193], v[190:191], off
	s_add_i32 s8, s88, 0xffffff81
	s_cmp_le_u32 s8, s7
	s_cbranch_scc0 .Latta_slow1
	s_add_i32 s12, s88, 0xffffff41
	s_cmp_le_i32 s12, s7
	s_cbranch_scc0 .Latta_slow1
	s_sub_i32 s10, s88, 64
	s_cmp_le_u32 s10, s90
	s_cbranch_scc0 .Latta_slow1
	ds_read_b128 v[66:69], v232
	ds_read_b128 v[70:73], v232 offset:32
	ds_read_b128 v[74:77], v232 offset:64
	ds_read_b128 v[78:81], v232 offset:96
	ds_read_b128 v[234:237], v218 offset:49152
	ds_read_b128 v[238:241], v218 offset:57344
	ds_read_b128 v[82:85], v232 offset:128
	ds_read_b128 v[86:89], v232 offset:160
	ds_read_b128 v[90:93], v232 offset:192
	ds_read_b128 v[94:97], v232 offset:224
	ds_read_b128 v[246:249], v219 offset:49152
	ds_read_b128 v[250:253], v219 offset:57344
	v_exp_f32_e32 v114, v114
	v_exp_f32_e32 v115, v115
	v_exp_f32_e32 v116, v116
	v_exp_f32_e32 v117, v117
	v_exp_f32_e32 v118, v118
	v_exp_f32_e32 v119, v119
	s_waitcnt lgkmcnt(7)
	v_mfma_f32_32x32x16_bf16 v[66:81], v[234:237], v[158:161], v[66:81]
	ds_read_b128 v[234:237], v220 offset:49152
	v_exp_f32_e32 v120, v120
	v_exp_f32_e32 v121, v121
	v_exp_f32_e32 v122, v122
	v_exp_f32_e32 v123, v123
	s_waitcnt lgkmcnt(3)
	v_mfma_f32_32x32x16_bf16 v[82:97], v[238:241], v[158:161], v[82:97]
	ds_read_b128 v[238:241], v220 offset:57344
	v_exp_f32_e32 v124, v124
	v_exp_f32_e32 v125, v125
	v_exp_f32_e32 v126, v126
	v_exp_f32_e32 v127, v127
	s_waitcnt lgkmcnt(3)
	v_mfma_f32_32x32x16_bf16 v[66:81], v[246:249], v[154:157], v[66:81]
	ds_read_b128 v[246:249], v221 offset:49152
	v_exp_f32_e32 v128, v128
	v_exp_f32_e32 v129, v129
	v_pk_add_f32 v[162:163], v[100:101], v[116:117]
	v_pk_add_f32 v[164:165], v[98:99], v[114:115]
	s_waitcnt lgkmcnt(3)
	v_mfma_f32_32x32x16_bf16 v[82:97], v[250:253], v[154:157], v[82:97]
	ds_read_b128 v[250:253], v221 offset:57344
	v_pk_add_f32 v[166:167], v[118:119], v[102:103]
	v_pk_add_f32 v[168:169], v[120:121], v[104:105]
	v_pk_add_f32 v[164:165], v[166:167], v[164:165]
	v_pk_add_f32 v[162:163], v[168:169], v[162:163]
	s_waitcnt lgkmcnt(3)
	v_mfma_f32_32x32x16_bf16 v[66:81], v[234:237], v[150:153], v[66:81]
	ds_read_b128 v[234:237], v218 offset:49280
	v_pk_add_f32 v[166:167], v[124:125], v[108:109]
	v_pk_add_f32 v[168:169], v[122:123], v[106:107]
	v_pk_add_f32 v[162:163], v[166:167], v[162:163]
	v_pk_add_f32 v[164:165], v[168:169], v[164:165]
	s_waitcnt lgkmcnt(3)
	v_mfma_f32_32x32x16_bf16 v[82:97], v[238:241], v[150:153], v[82:97]
	ds_read_b128 v[238:241], v218 offset:57472
	v_pk_add_f32 v[166:167], v[126:127], v[110:111]
	v_pk_add_f32 v[168:169], v[128:129], v[112:113]
	v_pk_add_f32 v[164:165], v[166:167], v[164:165]
	v_pk_add_f32 v[162:163], v[168:169], v[162:163]
	s_waitcnt lgkmcnt(3)
	v_mfma_f32_32x32x16_bf16 v[66:81], v[246:249], v[146:149], v[66:81]
	ds_read_b128 v[246:249], v219 offset:49280
	s_nop 0
	v_pk_mov_b32 v[166:167], v[164:165], v[162:163] op_sel:[1,0]
	v_mov_b32_e32 v165, v163
	v_pk_add_f32 v[162:163], v[166:167], v[164:165]
	s_waitcnt lgkmcnt(3)
	v_mfma_f32_32x32x16_bf16 v[82:97], v[250:253], v[146:149], v[82:97]
	ds_read_b128 v[250:253], v219 offset:57472
	s_nop 0
	v_pk_add_f32 v[162:163], v[162:163], v[162:163] op_sel:[0,1] op_sel_hi:[1,0]
	s_nop 0
	v_mov_b32_e32 v163, v162
	s_waitcnt lgkmcnt(3)
	v_mfma_f32_32x32x16_bf16 v[66:81], v[234:237], v[142:145], v[66:81]
	ds_read_b128 v[234:237], v220 offset:49280
	s_nop 1
	v_permlane32_swap_b32_e32 v162, v163
	v_add_f32_e32 v242, v162, v163
	v_fmac_f32_e32 v242, v204, v230
	s_waitcnt lgkmcnt(3)
	v_mfma_f32_32x32x16_bf16 v[82:97], v[238:241], v[142:145], v[82:97]
	ds_read_b128 v[238:241], v220 offset:57472
	v_cvt_pk_bf16_f32 v162, v98, v99
	v_cvt_pk_bf16_f32 v163, v100, v101
	v_cvt_pk_bf16_f32 v164, v102, v103
	v_cvt_pk_bf16_f32 v165, v104, v105
	s_waitcnt lgkmcnt(3)
	v_mfma_f32_32x32x16_bf16 v[66:81], v[246:249], v[138:141], v[66:81]
	ds_read_b128 v[246:249], v221 offset:49280
	v_cvt_pk_bf16_f32 v166, v106, v107
	v_cvt_pk_bf16_f32 v167, v108, v109
	v_cvt_pk_bf16_f32 v168, v110, v111
	v_cvt_pk_bf16_f32 v169, v112, v113
	s_waitcnt lgkmcnt(3)
	v_mfma_f32_32x32x16_bf16 v[82:97], v[250:253], v[138:141], v[82:97]
	ds_read_b128 v[250:253], v221 offset:57472
	v_cvt_pk_bf16_f32 v170, v114, v115
	v_cvt_pk_bf16_f32 v171, v116, v117
	v_cvt_pk_bf16_f32 v172, v118, v119
	v_cvt_pk_bf16_f32 v173, v120, v121
	s_waitcnt lgkmcnt(3)
	v_mfma_f32_32x32x16_bf16 v[66:81], v[234:237], v[134:137], v[66:81]
	v_cvt_pk_bf16_f32 v174, v122, v123
	v_cvt_pk_bf16_f32 v175, v124, v125
	v_cvt_pk_bf16_f32 v176, v126, v127
	v_cvt_pk_bf16_f32 v177, v128, v129
	s_waitcnt lgkmcnt(2)
	v_mfma_f32_32x32x16_bf16 v[82:97], v[238:241], v[134:137], v[82:97]
	s_nop 0
	v_permlane32_swap_b32_e32 v162, v164
	v_permlane32_swap_b32_e32 v163, v165
	v_permlane32_swap_b32_e32 v166, v168
	s_waitcnt lgkmcnt(1)
	v_mfma_f32_32x32x16_bf16 v[66:81], v[246:249], v[130:133], v[66:81]
	v_permlane32_swap_b32_e32 v167, v169
	v_permlane32_swap_b32_e32 v170, v172
	v_permlane32_swap_b32_e32 v171, v173
	s_waitcnt lgkmcnt(0)
; __device__ __forceinline__ void partialSM(f32x16& p0, f32x16& p1, float& m_reg, float& mn, float& alpha) {
;     float pmax = p0[0];
; #pragma unroll
;     for (int r = 1; r < 16; ++r) pmax = fmaxf(pmax, p0[r]);
; #pragma unroll
;     for (int r = 0; r < 16; ++r) pmax = fmaxf(pmax, p1[r]);
;     { auto rr = __builtin_amdgcn_permlane32_swap(__float_as_uint(pmax), __float_as_uint(pmax), false, false); pmax = fmaxf(__uint_as_float(rr[0]), __uint_as_float(rr[1])); }
;     constexpr float C2 = 1.4426950408889634f * SCALE;
;     if (__builtin_expect(__all((pmax - m_reg) * SCALE <= THR), 1)) { mn = m_reg; alpha = 1.f; }
;     else { mn = fmaxf(m_reg, pmax); alpha = __builtin_amdgcn_exp2f((m_reg - mn) * C2); m_reg = mn; }
;     const float mnL = -mn * C2;
; #pragma unroll
;     for (int r = 0; r < 16; ++r) p0[r] = fmaf(p0[r], C2, mnL);
; #pragma unroll
;     for (int r = 0; r < 16; ++r) p1[r] = fmaf(p1[r], C2, mnL);
; #pragma unroll
;     for (int r = 0; r < 16; ++r) p0[r] = __builtin_amdgcn_exp2f(p0[r]);
; }
; template <int VB>
; __device__ __forceinline__ void pv_tile(f32x16* o, int vb0, bf16x8 pa0, bf16x8 pa1, bf16x8 pa2, bf16x8 pa3) {
;     ...
;     PV_D0(0); PV_D0(1); PV_D0(2); PV_D0(3);
	v_mfma_f32_32x32x16_bf16 v[82:97], v[250:253], v[130:133], v[82:97]
	v_permlane32_swap_b32_e32 v174, v176
	v_permlane32_swap_b32_e32 v175, v177
	v_mov_b32_e32 v230, v242
	ds_read_b64_tr_b16 v[234:235], v212 offset:0
	ds_read_b64_tr_b16 v[236:237], v212 offset:0x800
	ds_read_b64_tr_b16 v[238:239], v212 offset:0x1000
	ds_read_b64_tr_b16 v[240:241], v212 offset:0x1800
	ds_read_b64_tr_b16 v[246:247], v212 offset:0x2000
	ds_read_b64_tr_b16 v[248:249], v212 offset:0x2800
	ds_read_b64_tr_b16 v[250:251], v212 offset:0x3000
	ds_read_b64_tr_b16 v[252:253], v212 offset:0x3800
	s_waitcnt lgkmcnt(0)
	s_nop 0
	v_mfma_f32_32x32x16_bf16 v[34:49], v[162:165], v[234:237], v[34:49]
	ds_read_b64_tr_b16 v[234:235], v212 offset:0x200
	ds_read_b64_tr_b16 v[236:237], v212 offset:0xa00
	v_mfma_f32_32x32x16_bf16 v[34:49], v[166:169], v[238:241], v[34:49]
	ds_read_b64_tr_b16 v[238:239], v212 offset:0x1200
	ds_read_b64_tr_b16 v[240:241], v212 offset:0x1a00
	v_max_f32_e32 v233, v67, v67
	v_max_f32_e32 v206, v66, v66
	v_max_f32_e32 v233, v206, v233
	v_max3_f32 v233, v233, v68, v69
	v_max3_f32 v233, v233, v70, v71
	v_max3_f32 v233, v233, v72, v73
	v_mfma_f32_32x32x16_bf16 v[34:49], v[170:173], v[246:249], v[34:49]
	ds_read_b64_tr_b16 v[246:247], v212 offset:0x2200
	ds_read_b64_tr_b16 v[248:249], v212 offset:0x2a00
	v_max3_f32 v233, v233, v74, v75
	v_max3_f32 v233, v233, v76, v77
	v_max3_f32 v233, v233, v78, v79
	v_max3_f32 v233, v233, v80, v81
	v_max3_f32 v233, v233, v82, v83
	v_max3_f32 v233, v233, v84, v85
	v_mfma_f32_32x32x16_bf16 v[34:49], v[174:177], v[250:253], v[34:49]
	ds_read_b64_tr_b16 v[250:251], v212 offset:0x3200
	ds_read_b64_tr_b16 v[252:253], v212 offset:0x3a00
	v_max3_f32 v233, v233, v86, v87
	v_max3_f32 v233, v233, v88, v89
	v_max3_f32 v233, v233, v90, v91
	v_max3_f32 v233, v233, v92, v93
	v_max3_f32 v233, v233, v94, v95
	v_max3_f32 v233, v233, v96, v97
	s_waitcnt lgkmcnt(0)
	v_mfma_f32_32x32x16_bf16 v[50:65], v[162:165], v[234:237], v[50:65]
	ds_read_b64_tr_b16 v[234:235], v212 offset:0x400
	ds_read_b64_tr_b16 v[236:237], v212 offset:0xc00
	v_mov_b32_e32 v206, v233
	s_nop 1
	v_permlane32_swap_b32_e32 v233, v206
	v_max_f32_e32 v206, v206, v206
	v_max_f32_e32 v233, v233, v233
	v_mfma_f32_32x32x16_bf16 v[50:65], v[166:169], v[238:241], v[50:65]
	ds_read_b64_tr_b16 v[238:239], v212 offset:0x1400
	ds_read_b64_tr_b16 v[240:241], v212 offset:0x1c00
	v_max_f32_e32 v233, v233, v206
	v_sub_f32_e32 v206, v233, v229
	v_mul_f32_e32 v206, 0x3db504f3, v206
	v_cmp_ge_f32_e32 vcc, s93, v206
	v_max_f32_e32 v206, v229, v229
	v_mfma_f32_32x32x16_bf16 v[50:65], v[170:173], v[246:249], v[50:65]
	ds_read_b64_tr_b16 v[246:247], v212 offset:0x2400
	ds_read_b64_tr_b16 v[248:249], v212 offset:0x2c00
	v_max_f32_e32 v233, v206, v233
	v_sub_f32_e32 v206, v229, v233
	v_mul_f32_e32 v206, 0x3e0293ee, v206
	v_exp_f32_e32 v206, v206
	s_cmp_eq_u64 vcc, exec
	v_mfma_f32_32x32x16_bf16 v[50:65], v[174:177], v[250:253], v[50:65]
	ds_read_b64_tr_b16 v[250:251], v212 offset:0x3400
	ds_read_b64_tr_b16 v[252:253], v212 offset:0x3c00
	s_cselect_b64 vcc, -1, 0
	v_cndmask_b32_e32 v229, v233, v229, vcc
	v_cndmask_b32_e64 v233, v206, 1.0, vcc
	v_mul_f32_e32 v206, 0xbe0293ee, v229
	v_mov_b32_e32 v207, v206
	s_waitcnt lgkmcnt(0)
	v_mfma_f32_32x32x16_bf16 v[18:33], v[162:165], v[234:237], v[18:33]
	ds_read_b64_tr_b16 v[234:235], v212 offset:0x600
	ds_read_b64_tr_b16 v[236:237], v212 offset:0xe00
	v_fmamk_f32 v66, v66, 0x3e0293ee, v206
	v_fmamk_f32 v67, v67, 0x3e0293ee, v206
	v_fmamk_f32 v68, v68, 0x3e0293ee, v206
	v_fmamk_f32 v69, v69, 0x3e0293ee, v206
	v_fmamk_f32 v70, v70, 0x3e0293ee, v206
	v_mfma_f32_32x32x16_bf16 v[18:33], v[166:169], v[238:241], v[18:33]
	ds_read_b64_tr_b16 v[238:239], v212 offset:0x1600
	ds_read_b64_tr_b16 v[240:241], v212 offset:0x1e00
	v_fmamk_f32 v71, v71, 0x3e0293ee, v206
	v_fmamk_f32 v72, v72, 0x3e0293ee, v206
	v_fmamk_f32 v73, v73, 0x3e0293ee, v206
	v_fmamk_f32 v74, v74, 0x3e0293ee, v206
	v_fmamk_f32 v75, v75, 0x3e0293ee, v206
	v_mfma_f32_32x32x16_bf16 v[18:33], v[170:173], v[246:249], v[18:33]
	ds_read_b64_tr_b16 v[246:247], v212 offset:0x2600
	ds_read_b64_tr_b16 v[248:249], v212 offset:0x2e00
	v_fmamk_f32 v76, v76, 0x3e0293ee, v206
	v_fmamk_f32 v77, v77, 0x3e0293ee, v206
	v_fmamk_f32 v78, v78, 0x3e0293ee, v206
	v_fmamk_f32 v79, v79, 0x3e0293ee, v206
	v_fmamk_f32 v80, v80, 0x3e0293ee, v206
	v_mfma_f32_32x32x16_bf16 v[18:33], v[174:177], v[250:253], v[18:33]
	ds_read_b64_tr_b16 v[250:251], v212 offset:0x3600
	ds_read_b64_tr_b16 v[252:253], v212 offset:0x3e00
	v_fmac_f32_e32 v207, 0x3e0293ee, v81
	v_exp_f32_e32 v66, v66
	v_exp_f32_e32 v67, v67
	v_exp_f32_e32 v68, v68
	v_exp_f32_e32 v69, v69
	s_waitcnt lgkmcnt(0)
	v_mfma_f32_32x32x16_bf16 v[2:17], v[162:165], v[234:237], v[2:17]
	v_exp_f32_e32 v70, v70
	v_exp_f32_e32 v71, v71
	v_exp_f32_e32 v72, v72
	v_exp_f32_e32 v73, v73
	v_exp_f32_e32 v74, v74
	v_mfma_f32_32x32x16_bf16 v[2:17], v[166:169], v[238:241], v[2:17]
	v_exp_f32_e32 v75, v75
	v_exp_f32_e32 v76, v76
	v_exp_f32_e32 v77, v77
	v_exp_f32_e32 v78, v78
	v_exp_f32_e32 v79, v79
	v_mfma_f32_32x32x16_bf16 v[2:17], v[170:173], v[246:249], v[2:17]
	v_exp_f32_e32 v80, v80
	v_exp_f32_e32 v81, v207
	v_pk_fma_f32 v[96:97], v[96:97], s[94:95], v[206:207] op_sel_hi:[1,0,0]
	v_pk_fma_f32 v[94:95], v[94:95], s[94:95], v[206:207] op_sel_hi:[1,0,0]
	v_pk_fma_f32 v[92:93], v[92:93], s[94:95], v[206:207] op_sel_hi:[1,0,0]
	v_mfma_f32_32x32x16_bf16 v[2:17], v[174:177], v[250:253], v[2:17]
	v_pk_fma_f32 v[90:91], v[90:91], s[94:95], v[206:207] op_sel_hi:[1,0,0]
	v_pk_fma_f32 v[88:89], v[88:89], s[94:95], v[206:207] op_sel_hi:[1,0,0]
	v_pk_fma_f32 v[86:87], v[86:87], s[94:95], v[206:207] op_sel_hi:[1,0,0]
	v_pk_fma_f32 v[84:85], v[84:85], s[94:95], v[206:207] op_sel_hi:[1,0,0]
	v_pk_fma_f32 v[82:83], v[82:83], s[94:95], v[206:207] op_sel_hi:[1,0,0]
	s_mov_b64 s[8:9], 0
	s_branch .Latta_539
; #define LAS __attribute__((address_space(3)))
; template <int KB>
; __device__ __forceinline__ void qkt(f32x16& p0, f32x16& p1, lptr K_lds, int r32, int hi, const bf16x8* qr, const LAS float* blk) {
;     { const LAS f32x4* bp = (const LAS f32x4*)blk;
;       const f32x4 a0 = bp[0], a1 = bp[2], a2 = bp[4], a3 = bp[6], c0 = bp[8], c1 = bp[10], c2 = bp[12], c3 = bp[14];
;       p0 = (f32x16){a0[0], a0[1], a0[2], a0[3], a1[0], a1[1], a1[2], a1[3], a2[0], a2[1], a2[2], a2[3], a3[0], a3[1], a3[2], a3[3]};
;       p1 = (f32x16){c0[0], c0[1], c0[2], c0[3], c1[0], c1[1], c1[2], c1[3], c2[0], c2[1], c2[2], c2[3], c3[0], c3[1], c3[2], c3[3]}; }
;     lptr kb[4];
; #pragma unroll
;     for (int dd = 0; dd < 4; ++dd) kb[dd] = K_lds + KB * SHM_K + KSWZ(r32, (dd * 16 + hi * 8) * 2);
; #pragma unroll
;     for (int d0 = 0; d0 < 8; ++d0) { lptr a = kb[d0 & 3] + (d0 >> 2) * 128;
;         bf16x8 b0 = *(const LAS bf16x8*)(a);
;         bf16x8 b1 = *(const LAS bf16x8*)(a + 32 * 256);
;         p0 = __builtin_amdgcn_mfma_f32_32x32x16_bf16(b0, qr[d0], p0, 0, 0, 0);
;         p1 = __builtin_amdgcn_mfma_f32_32x32x16_bf16(b1, qr[d0], p1, 0, 0, 0); }
; }
.Latta_slow1:
	s_add_i32 s8, s88, 0xffffff81
	s_cmp_le_u32 s8, s7
	s_cselect_b64 s[10:11], -1, 0
	s_cmp_gt_u32 s8, s7
	s_cbranch_scc1 .Latta_531
	ds_read_b128 v[66:69], v232
	ds_read_b128 v[70:73], v232 offset:32
	ds_read_b128 v[74:77], v232 offset:64
	ds_read_b128 v[78:81], v232 offset:96
	ds_read_b128 v[162:165], v218 offset:49152
	ds_read_b128 v[166:169], v218 offset:57344
	ds_read_b128 v[82:85], v232 offset:128
	ds_read_b128 v[86:89], v232 offset:160
	ds_read_b128 v[90:93], v232 offset:192
	ds_read_b128 v[94:97], v232 offset:224
	ds_read_b128 v[170:173], v219 offset:49152
	ds_read_b128 v[174:177], v219 offset:57344
	ds_read_b128 v[234:237], v220 offset:49152
	ds_read_b128 v[238:241], v220 offset:57344
	ds_read_b128 v[246:249], v221 offset:49152
	s_waitcnt lgkmcnt(10)
	v_mfma_f32_32x32x16_bf16 v[66:81], v[162:165], v[158:161], v[66:81]
	ds_read_b128 v[250:253], v221 offset:57344
	s_waitcnt lgkmcnt(6)
	v_mfma_f32_32x32x16_bf16 v[82:97], v[166:169], v[158:161], v[82:97]
	ds_read_b128 v[162:165], v218 offset:49280
	s_waitcnt lgkmcnt(6)
	v_mfma_f32_32x32x16_bf16 v[66:81], v[170:173], v[154:157], v[66:81]
	ds_read_b128 v[166:169], v218 offset:57472
	s_waitcnt lgkmcnt(6)
	v_mfma_f32_32x32x16_bf16 v[82:97], v[174:177], v[154:157], v[82:97]
	ds_read_b128 v[170:173], v219 offset:49280
	s_waitcnt lgkmcnt(6)
	v_mfma_f32_32x32x16_bf16 v[66:81], v[234:237], v[150:153], v[66:81]
	ds_read_b128 v[174:177], v219 offset:57472
	s_waitcnt lgkmcnt(6)
	v_mfma_f32_32x32x16_bf16 v[82:97], v[238:241], v[150:153], v[82:97]
	ds_read_b128 v[234:237], v220 offset:49280
	s_waitcnt lgkmcnt(6)
	v_mfma_f32_32x32x16_bf16 v[66:81], v[246:249], v[146:149], v[66:81]
	ds_read_b128 v[238:241], v220 offset:57472
	s_waitcnt lgkmcnt(6)
	v_mfma_f32_32x32x16_bf16 v[82:97], v[250:253], v[146:149], v[82:97]
	ds_read_b128 v[246:249], v221 offset:49280
	s_waitcnt lgkmcnt(6)
	v_mfma_f32_32x32x16_bf16 v[66:81], v[162:165], v[142:145], v[66:81]
	ds_read_b128 v[250:253], v221 offset:57472
	s_waitcnt lgkmcnt(6)
	v_mfma_f32_32x32x16_bf16 v[82:97], v[166:169], v[142:145], v[82:97]
	s_waitcnt lgkmcnt(5)
	v_mfma_f32_32x32x16_bf16 v[66:81], v[170:173], v[138:141], v[66:81]
	s_waitcnt lgkmcnt(4)
	v_mfma_f32_32x32x16_bf16 v[82:97], v[174:177], v[138:141], v[82:97]
	s_waitcnt lgkmcnt(3)
	v_mfma_f32_32x32x16_bf16 v[66:81], v[234:237], v[134:137], v[66:81]
	s_waitcnt lgkmcnt(2)
	v_mfma_f32_32x32x16_bf16 v[82:97], v[238:241], v[134:137], v[82:97]
	s_waitcnt lgkmcnt(1)
	v_mfma_f32_32x32x16_bf16 v[66:81], v[246:249], v[130:133], v[66:81]
	s_waitcnt lgkmcnt(0)
	v_mfma_f32_32x32x16_bf16 v[82:97], v[250:253], v[130:133], v[82:97]

; #define LAS __attribute__((address_space(3)))
; __device__ __forceinline__ void finishSM(f32x16& p0, f32x16& p1, float alpha, float& l_reg, bf16x8& pa0, bf16x8& pa1, bf16x8& pa2, bf16x8& pa3) {
; #pragma unroll
;     for (int r = 0; r < 16; ++r) p1[r] = __builtin_amdgcn_exp2f(p1[r]);
;     f32x4 s4 = (f32x4){p0[0], p0[1], p0[2], p0[3]} + (f32x4){p1[0], p1[1], p1[2], p1[3]};
; #pragma unroll
;     for (int r = 4; r < 16; r += 4) s4 += (f32x4){p0[r], p0[r + 1], p0[r + 2], p0[r + 3]} + (f32x4){p1[r], p1[r + 1], p1[r + 2], p1[r + 3]};
;     float ps = (s4[0] + s4[1]) + (s4[2] + s4[3]);
;     { auto rr = __builtin_amdgcn_permlane32_swap(__float_as_uint(ps), __float_as_uint(ps), false, false); ps = __uint_as_float(rr[0]) + __uint_as_float(rr[1]); }
;     l_reg = l_reg * alpha + ps;
;     ...
;     PK4(p0, 0, pa0); PK4(p0, 8, pa1); PK4(p1, 0, pa2); PK4(p1, 8, pa3);
;     ...
; }
; template <int KB>
; __device__ __forceinline__ void qkt(f32x16& p0, f32x16& p1, lptr K_lds, int r32, int hi, const bf16x8* qr, const LAS float* blk) {
;     { const LAS f32x4* bp = (const LAS f32x4*)blk;
;       const f32x4 a0 = bp[0], a1 = bp[2], a2 = bp[4], a3 = bp[6], c0 = bp[8], c1 = bp[10], c2 = bp[12], c3 = bp[14];
;       p0 = (f32x16){a0[0], a0[1], a0[2], a0[3], a1[0], a1[1], a1[2], a1[3], a2[0], a2[1], a2[2], a2[3], a3[0], a3[1], a3[2], a3[3]};
;       p1 = (f32x16){c0[0], c0[1], c0[2], c0[3], c1[0], c1[1], c1[2], c1[3], c2[0], c2[1], c2[2], c2[3], c3[0], c3[1], c3[2], c3[3]}; }
;     lptr kb[4];
; #pragma unroll
;     for (int dd = 0; dd < 4; ++dd) kb[dd] = K_lds + KB * SHM_K + KSWZ(r32, (dd * 16 + hi * 8) * 2);
; #pragma unroll
;     for (int d0 = 0; d0 < 8; ++d0) { lptr a = kb[d0 & 3] + (d0 >> 2) * 128;
;         bf16x8 b0 = *(const LAS bf16x8*)(a);
;         bf16x8 b1 = *(const LAS bf16x8*)(a + 32 * 256);
;         p0 = __builtin_amdgcn_mfma_f32_32x32x16_bf16(b0, qr[d0], p0, 0, 0, 0);
;         p1 = __builtin_amdgcn_mfma_f32_32x32x16_bf16(b1, qr[d0], p1, 0, 0, 0); }
; }
.Latta_noload2:
	s_cmp_le_i32 s12, s7
	s_cbranch_scc0 .Latta_slow2
	s_cmp_eq_u64 s[8:9], 0
	s_cbranch_scc0 .Latta_slow2
	s_cmp_le_i32 s88, s90
	s_cbranch_scc0 .Latta_slow2
	ds_read_b128 v[98:101], v232 offset:256
	ds_read_b128 v[102:105], v232 offset:288
	ds_read_b128 v[106:109], v232 offset:320
	ds_read_b128 v[110:113], v232 offset:352
	ds_read_b128 v[234:237], v218 offset:32768
	ds_read_b128 v[238:241], v218 offset:40960
	ds_read_b128 v[114:117], v232 offset:384
	ds_read_b128 v[118:121], v232 offset:416
	ds_read_b128 v[122:125], v232 offset:448
	ds_read_b128 v[126:129], v232 offset:480
	ds_read_b128 v[246:249], v219 offset:32768
	ds_read_b128 v[250:253], v219 offset:40960
	v_exp_f32_e32 v82, v82
	v_exp_f32_e32 v83, v83
	v_exp_f32_e32 v84, v84
	v_exp_f32_e32 v85, v85
	v_exp_f32_e32 v86, v86
	v_exp_f32_e32 v87, v87
	s_waitcnt lgkmcnt(7)
	v_mfma_f32_32x32x16_bf16 v[98:113], v[234:237], v[158:161], v[98:113]
	ds_read_b128 v[234:237], v220 offset:32768
	v_exp_f32_e32 v88, v88
	v_exp_f32_e32 v89, v89
	v_exp_f32_e32 v90, v90
	v_exp_f32_e32 v91, v91
	s_waitcnt lgkmcnt(3)
	v_mfma_f32_32x32x16_bf16 v[114:129], v[238:241], v[158:161], v[114:129]
	ds_read_b128 v[238:241], v220 offset:40960
	v_exp_f32_e32 v92, v92
	v_exp_f32_e32 v93, v93
	v_exp_f32_e32 v94, v94
	v_exp_f32_e32 v95, v95
	s_waitcnt lgkmcnt(3)
	v_mfma_f32_32x32x16_bf16 v[98:113], v[246:249], v[154:157], v[98:113]
	ds_read_b128 v[246:249], v221 offset:32768
	v_exp_f32_e32 v96, v96
	v_exp_f32_e32 v97, v97
	v_pk_add_f32 v[162:163], v[68:69], v[84:85]
	v_pk_add_f32 v[164:165], v[66:67], v[82:83]
	s_waitcnt lgkmcnt(3)
	v_mfma_f32_32x32x16_bf16 v[114:129], v[250:253], v[154:157], v[114:129]
	ds_read_b128 v[250:253], v221 offset:40960
	v_pk_add_f32 v[166:167], v[70:71], v[86:87]
	v_pk_add_f32 v[168:169], v[72:73], v[88:89]
	v_pk_add_f32 v[164:165], v[166:167], v[164:165]
	v_pk_add_f32 v[162:163], v[168:169], v[162:163]
	s_waitcnt lgkmcnt(3)
	v_mfma_f32_32x32x16_bf16 v[98:113], v[234:237], v[150:153], v[98:113]
	ds_read_b128 v[234:237], v218 offset:32896
	v_pk_add_f32 v[166:167], v[76:77], v[92:93]
	v_pk_add_f32 v[168:169], v[74:75], v[90:91]
	v_pk_add_f32 v[162:163], v[166:167], v[162:163]
	v_pk_add_f32 v[164:165], v[168:169], v[164:165]
	s_waitcnt lgkmcnt(3)
	v_mfma_f32_32x32x16_bf16 v[114:129], v[238:241], v[150:153], v[114:129]
	ds_read_b128 v[238:241], v218 offset:41088
	v_pk_add_f32 v[166:167], v[78:79], v[94:95]
	v_pk_add_f32 v[168:169], v[80:81], v[96:97]
	v_pk_add_f32 v[164:165], v[166:167], v[164:165]
	v_pk_add_f32 v[162:163], v[168:169], v[162:163]
	s_waitcnt lgkmcnt(3)
	v_mfma_f32_32x32x16_bf16 v[98:113], v[246:249], v[146:149], v[98:113]
	ds_read_b128 v[246:249], v219 offset:32896
	s_nop 0
	v_pk_mov_b32 v[166:167], v[164:165], v[162:163] op_sel:[1,0]
	v_mov_b32_e32 v165, v163
	v_pk_add_f32 v[162:163], v[166:167], v[164:165]
	s_waitcnt lgkmcnt(3)
	v_mfma_f32_32x32x16_bf16 v[114:129], v[250:253], v[146:149], v[114:129]
	ds_read_b128 v[250:253], v219 offset:41088
	s_nop 0
	v_pk_add_f32 v[162:163], v[162:163], v[162:163] op_sel:[0,1] op_sel_hi:[1,0]
	s_nop 0
	v_mov_b32_e32 v163, v162
	s_waitcnt lgkmcnt(3)
	v_mfma_f32_32x32x16_bf16 v[98:113], v[234:237], v[142:145], v[98:113]
	ds_read_b128 v[234:237], v220 offset:32896
	s_nop 1
	v_permlane32_swap_b32_e32 v162, v163
	v_add_f32_e32 v242, v162, v163
	v_fmac_f32_e32 v242, v230, v233
	s_waitcnt lgkmcnt(3)
	v_mfma_f32_32x32x16_bf16 v[114:129], v[238:241], v[142:145], v[114:129]
	ds_read_b128 v[238:241], v220 offset:41088
	v_cvt_pk_bf16_f32 v162, v66, v67
	v_cvt_pk_bf16_f32 v163, v68, v69
	v_cvt_pk_bf16_f32 v164, v70, v71
	v_cvt_pk_bf16_f32 v165, v72, v73
	s_waitcnt lgkmcnt(3)
	v_mfma_f32_32x32x16_bf16 v[98:113], v[246:249], v[138:141], v[98:113]
	ds_read_b128 v[246:249], v221 offset:32896
	v_cvt_pk_bf16_f32 v166, v74, v75
	v_cvt_pk_bf16_f32 v167, v76, v77
	v_cvt_pk_bf16_f32 v168, v78, v79
	v_cvt_pk_bf16_f32 v169, v80, v81
	s_waitcnt lgkmcnt(3)
	v_mfma_f32_32x32x16_bf16 v[114:129], v[250:253], v[138:141], v[114:129]
	ds_read_b128 v[250:253], v221 offset:41088
	v_cvt_pk_bf16_f32 v170, v82, v83
	v_cvt_pk_bf16_f32 v171, v84, v85
	v_cvt_pk_bf16_f32 v172, v86, v87
	v_cvt_pk_bf16_f32 v173, v88, v89
	s_waitcnt lgkmcnt(3)
	v_mfma_f32_32x32x16_bf16 v[98:113], v[234:237], v[134:137], v[98:113]
	v_cvt_pk_bf16_f32 v174, v90, v91
	v_cvt_pk_bf16_f32 v175, v92, v93
	v_cvt_pk_bf16_f32 v176, v94, v95
	v_cvt_pk_bf16_f32 v177, v96, v97
	s_waitcnt lgkmcnt(2)
	v_mfma_f32_32x32x16_bf16 v[114:129], v[238:241], v[134:137], v[114:129]
	s_nop 0
	v_permlane32_swap_b32_e32 v162, v164
	v_permlane32_swap_b32_e32 v163, v165
	v_permlane32_swap_b32_e32 v166, v168
	s_waitcnt lgkmcnt(1)
	v_mfma_f32_32x32x16_bf16 v[98:113], v[246:249], v[130:133], v[98:113]
	v_permlane32_swap_b32_e32 v167, v169
	v_permlane32_swap_b32_e32 v170, v172
	v_permlane32_swap_b32_e32 v171, v173
	s_waitcnt lgkmcnt(0)
	v_mfma_f32_32x32x16_bf16 v[114:129], v[250:253], v[130:133], v[114:129]
	v_permlane32_swap_b32_e32 v174, v176
	v_permlane32_swap_b32_e32 v175, v177
	v_mov_b32_e32 v230, v242
	ds_read_b64_tr_b16 v[204:205], v212 offset:0x4000
	ds_read_b64_tr_b16 v[206:207], v212 offset:0x4800
	ds_read_b64_tr_b16 v[234:235], v212 offset:0x5000
	ds_read_b64_tr_b16 v[236:237], v212 offset:0x5800
	ds_read_b64_tr_b16 v[238:239], v212 offset:0x6000
	ds_read_b64_tr_b16 v[240:241], v212 offset:0x6800
	ds_read_b64_tr_b16 v[246:247], v212 offset:0x7000
	ds_read_b64_tr_b16 v[248:249], v212 offset:0x7800
	s_waitcnt lgkmcnt(0)
; __device__ __forceinline__ void partialSM(f32x16& p0, f32x16& p1, float& m_reg, float& mn, float& alpha) {
;     float pmax = p0[0];
; #pragma unroll
;     for (int r = 1; r < 16; ++r) pmax = fmaxf(pmax, p0[r]);
; #pragma unroll
;     for (int r = 0; r < 16; ++r) pmax = fmaxf(pmax, p1[r]);
;     { auto rr = __builtin_amdgcn_permlane32_swap(__float_as_uint(pmax), __float_as_uint(pmax), false, false); pmax = fmaxf(__uint_as_float(rr[0]), __uint_as_float(rr[1])); }
;     constexpr float C2 = 1.4426950408889634f * SCALE;
;     if (__builtin_expect(__all((pmax - m_reg) * SCALE <= THR), 1)) { mn = m_reg; alpha = 1.f; }
;     else { mn = fmaxf(m_reg, pmax); alpha = __builtin_amdgcn_exp2f((m_reg - mn) * C2); m_reg = mn; }
;     const float mnL = -mn * C2;
; #pragma unroll
;     for (int r = 0; r < 16; ++r) p0[r] = fmaf(p0[r], C2, mnL);
; #pragma unroll
;     for (int r = 0; r < 16; ++r) p1[r] = fmaf(p1[r], C2, mnL);
; #pragma unroll
;     for (int r = 0; r < 16; ++r) p0[r] = __builtin_amdgcn_exp2f(p0[r]);
; }
; template <int VB>
; __device__ __forceinline__ void pv_tile(f32x16* o, int vb0, bf16x8 pa0, bf16x8 pa1, bf16x8 pa2, bf16x8 pa3) {
;     ...
;     PV_D0(0); PV_D0(1); PV_D0(2); PV_D0(3);
	s_nop 0
	v_mfma_f32_32x32x16_bf16 v[34:49], v[162:165], v[204:207], v[34:49]
	ds_read_b64_tr_b16 v[204:205], v212 offset:0x4200
	ds_read_b64_tr_b16 v[206:207], v212 offset:0x4a00
	v_mfma_f32_32x32x16_bf16 v[34:49], v[166:169], v[234:237], v[34:49]
	ds_read_b64_tr_b16 v[234:235], v212 offset:0x5200
	ds_read_b64_tr_b16 v[236:237], v212 offset:0x5a00
	v_max_f32_e32 v250, v99, v99
	v_max_f32_e32 v251, v98, v98
	v_max_f32_e32 v250, v251, v250
	v_max3_f32 v250, v250, v100, v101
	v_max3_f32 v250, v250, v102, v103
	v_max3_f32 v250, v250, v104, v105
	v_mfma_f32_32x32x16_bf16 v[34:49], v[170:173], v[238:241], v[34:49]
	ds_read_b64_tr_b16 v[238:239], v212 offset:0x6200
	ds_read_b64_tr_b16 v[240:241], v212 offset:0x6a00
	v_max3_f32 v250, v250, v106, v107
	v_max3_f32 v250, v250, v108, v109
	v_max3_f32 v250, v250, v110, v111
	v_max3_f32 v250, v250, v112, v113
	v_max3_f32 v250, v250, v114, v115
	v_max3_f32 v250, v250, v116, v117
	v_mfma_f32_32x32x16_bf16 v[34:49], v[174:177], v[246:249], v[34:49]
	ds_read_b64_tr_b16 v[246:247], v212 offset:0x7200
	ds_read_b64_tr_b16 v[248:249], v212 offset:0x7a00
	v_max3_f32 v250, v250, v118, v119
	v_max3_f32 v250, v250, v120, v121
	v_max3_f32 v250, v250, v122, v123
	v_max3_f32 v250, v250, v124, v125
	v_max3_f32 v250, v250, v126, v127
	v_max3_f32 v250, v250, v128, v129
	s_waitcnt lgkmcnt(0)
	v_mfma_f32_32x32x16_bf16 v[50:65], v[162:165], v[204:207], v[50:65]
	ds_read_b64_tr_b16 v[204:205], v212 offset:0x4400
	ds_read_b64_tr_b16 v[206:207], v212 offset:0x4c00
	v_mov_b32_e32 v251, v250
	s_nop 1
	v_permlane32_swap_b32_e32 v250, v251
	v_max_f32_e32 v251, v251, v251
	v_max_f32_e32 v250, v250, v250
	v_mfma_f32_32x32x16_bf16 v[50:65], v[166:169], v[234:237], v[50:65]
	ds_read_b64_tr_b16 v[234:235], v212 offset:0x5400
	ds_read_b64_tr_b16 v[236:237], v212 offset:0x5c00
	v_max_f32_e32 v250, v250, v251
	v_sub_f32_e32 v251, v250, v229
	v_mul_f32_e32 v251, 0x3db504f3, v251
	v_cmp_ge_f32_e32 vcc, s93, v251
	v_max_f32_e32 v251, v229, v229
	v_mfma_f32_32x32x16_bf16 v[50:65], v[170:173], v[238:241], v[50:65]
	ds_read_b64_tr_b16 v[238:239], v212 offset:0x6400
	ds_read_b64_tr_b16 v[240:241], v212 offset:0x6c00
	v_max_f32_e32 v250, v251, v250
	v_sub_f32_e32 v251, v229, v250
	v_mul_f32_e32 v251, 0x3e0293ee, v251
	v_exp_f32_e32 v251, v251
	s_cmp_eq_u64 vcc, exec
	v_mfma_f32_32x32x16_bf16 v[50:65], v[174:177], v[246:249], v[50:65]
	ds_read_b64_tr_b16 v[246:247], v212 offset:0x7400
	ds_read_b64_tr_b16 v[248:249], v212 offset:0x7c00
	s_cselect_b64 vcc, -1, 0
	v_cndmask_b32_e32 v229, v250, v229, vcc
	v_mul_f32_e32 v252, 0xbe0293ee, v229
	v_cndmask_b32_e64 v250, v251, 1.0, vcc
	v_mov_b32_e32 v251, v252
	s_waitcnt lgkmcnt(0)
	v_mfma_f32_32x32x16_bf16 v[18:33], v[162:165], v[204:207], v[18:33]
	ds_read_b64_tr_b16 v[204:205], v212 offset:0x4600
	ds_read_b64_tr_b16 v[206:207], v212 offset:0x4e00
	v_fmamk_f32 v98, v98, 0x3e0293ee, v252
	v_fmamk_f32 v99, v99, 0x3e0293ee, v252
	v_fmamk_f32 v100, v100, 0x3e0293ee, v252
	v_fmamk_f32 v101, v101, 0x3e0293ee, v252
	v_fmamk_f32 v102, v102, 0x3e0293ee, v252
	v_mfma_f32_32x32x16_bf16 v[18:33], v[166:169], v[234:237], v[18:33]
	ds_read_b64_tr_b16 v[234:235], v212 offset:0x5600
	ds_read_b64_tr_b16 v[236:237], v212 offset:0x5e00
	v_fmamk_f32 v103, v103, 0x3e0293ee, v252
	v_fmamk_f32 v104, v104, 0x3e0293ee, v252
	v_fmamk_f32 v105, v105, 0x3e0293ee, v252
	v_fmamk_f32 v106, v106, 0x3e0293ee, v252
	v_fmamk_f32 v107, v107, 0x3e0293ee, v252
	v_mfma_f32_32x32x16_bf16 v[18:33], v[170:173], v[238:241], v[18:33]
	ds_read_b64_tr_b16 v[238:239], v212 offset:0x6600
	ds_read_b64_tr_b16 v[240:241], v212 offset:0x6e00
	v_fmamk_f32 v108, v108, 0x3e0293ee, v252
	v_fmamk_f32 v109, v109, 0x3e0293ee, v252
	v_fmamk_f32 v110, v110, 0x3e0293ee, v252
	v_fmamk_f32 v111, v111, 0x3e0293ee, v252
	v_fmamk_f32 v112, v112, 0x3e0293ee, v252
	v_mfma_f32_32x32x16_bf16 v[18:33], v[174:177], v[246:249], v[18:33]
	ds_read_b64_tr_b16 v[246:247], v212 offset:0x7600
	ds_read_b64_tr_b16 v[248:249], v212 offset:0x7e00
	v_fmac_f32_e32 v251, 0x3e0293ee, v113
	v_exp_f32_e32 v98, v98
	v_exp_f32_e32 v99, v99
	v_exp_f32_e32 v100, v100
	v_exp_f32_e32 v101, v101
	s_waitcnt lgkmcnt(0)
	v_mfma_f32_32x32x16_bf16 v[2:17], v[162:165], v[204:207], v[2:17]
	v_exp_f32_e32 v102, v102
	v_exp_f32_e32 v103, v103
	v_exp_f32_e32 v104, v104
	v_exp_f32_e32 v105, v105
	v_exp_f32_e32 v106, v106
	v_mfma_f32_32x32x16_bf16 v[2:17], v[166:169], v[234:237], v[2:17]
	v_exp_f32_e32 v107, v107
	v_exp_f32_e32 v108, v108
	v_exp_f32_e32 v109, v109
	v_exp_f32_e32 v110, v110
	v_exp_f32_e32 v111, v111
	v_mfma_f32_32x32x16_bf16 v[2:17], v[170:173], v[238:241], v[2:17]
	v_exp_f32_e32 v112, v112
	v_exp_f32_e32 v113, v251
	v_pk_fma_f32 v[128:129], v[128:129], s[94:95], v[252:253] op_sel_hi:[1,0,0]
	v_pk_fma_f32 v[126:127], v[126:127], s[94:95], v[252:253] op_sel_hi:[1,0,0]
	v_pk_fma_f32 v[124:125], v[124:125], s[94:95], v[252:253] op_sel_hi:[1,0,0]
	v_mfma_f32_32x32x16_bf16 v[2:17], v[174:177], v[246:249], v[2:17]
	v_pk_fma_f32 v[122:123], v[122:123], s[94:95], v[252:253] op_sel_hi:[1,0,0]
	v_pk_fma_f32 v[120:121], v[120:121], s[94:95], v[252:253] op_sel_hi:[1,0,0]
	v_pk_fma_f32 v[118:119], v[118:119], s[94:95], v[252:253] op_sel_hi:[1,0,0]
	v_pk_fma_f32 v[116:117], v[116:117], s[94:95], v[252:253] op_sel_hi:[1,0,0]
	v_pk_fma_f32 v[114:115], v[114:115], s[94:95], v[252:253] op_sel_hi:[1,0,0]
	v_mov_b32_e32 v204, v250
	s_branch .Latta_555
